# per-group start offset applied at the start of P4 (inside the P3->P4 group sync) instead of the start of P3
# baseline (speedup 1.0000x reference)
; __device__ __forceinline__ unsigned xb_ld(unsigned* p)              { return __hip_atomic_load(p, __ATOMIC_RELAXED, __HIP_MEMORY_SCOPE_AGENT); }
; __device__ __forceinline__ unsigned xb_add(unsigned* p, unsigned v) { return __hip_atomic_fetch_add(p, v, __ATOMIC_RELAXED, __HIP_MEMORY_SCOPE_AGENT); }
; #define XB_SPIN(cond, bar) do { unsigned _sp = 0; while (cond) { __builtin_amdgcn_s_sleep(1); \
;     if ((++_sp & 255u) == 0u) { if (xb_ld(&(bar)[XB_TMO])) break; if (_sp > XB_SPIN_CAP) { atomicAdd(&(bar)[XB_TMO], 1u); break; } } } } while (0)
; #define SEAM(k) do { if (IN(k) && IN((k) + 1)) GRID_SYNC(); } while (0)
; __device__ __forceinline__ void xcd_barrier(const XcdBarrier& b) {
;     asm volatile("s_waitcnt vmcnt(0)" ::: "memory");
;     __syncthreads();
;     if (threadIdx.x == 0) {
;         unsigned* bar = b.bar;
;         __builtin_amdgcn_s_waitcnt(0);
;         unsigned nloc = b.st[0], nx = b.st[1];
;         if (nloc == 0u) { xcd_barrier_complete(bar, b.x, nloc, nx); b.st[0] = nloc; b.st[1] = nx; }
;         const unsigned old = xb_add(&bar[XB_XSUB(b.x)], 1u);
;         const unsigned gen = old / nloc;
;         if (old + 1u == (gen + 1u) * nloc) {
;             __builtin_amdgcn_fence(__ATOMIC_RELEASE, "agent");
;             asm volatile("s_waitcnt vmcnt(0)" ::: "memory");
;             const unsigned og = xb_add(&bar[XB_TOP], 1u);
;             const unsigned tg = og / nx;
;             if (og + 1u == (tg + 1u) * nx) xb_add(&bar[XB_TOPGEN], 1u);
;             else XB_SPIN(xb_ld(&bar[XB_TOPGEN]) == tg, bar);
;             __builtin_amdgcn_fence(__ATOMIC_ACQUIRE, "agent");
;             xb_add(&bar[XB_XGEN(b.x)], 1u);
;             asm volatile("s_waitcnt vmcnt(0)" ::: "memory");
;         } else {
;             XB_SPIN(xb_ld(&bar[XB_XGEN(b.x)]) == gen, bar);
;             __builtin_amdgcn_fence(__ATOMIC_ACQUIRE, "agent");
;             asm volatile("s_waitcnt vmcnt(0)" ::: "memory");
;         }
;     }
;     __syncthreads();
; }
; __global__ void __launch_bounds__(NTHR, 2) mk_fwd(MkArgs a) {
;     ...
;     SEAM(3);
.Lgb3_poll:
	s_sleep 1
	global_load_dword v2, v0, s[90:91] sc1
	s_waitcnt vmcnt(0)
	v_cmp_gt_u32_e32 vcc, 4, v2
	s_cbranch_vccnz .Lgb3_poll
	s_and_b32 s98, s97, 63
.Lstg4_loop:
	s_cmp_eq_u32 s98, 0
	s_cbranch_scc1 .Lstg4_done
	s_sleep 10
	s_sub_u32 s98, s98, 1
	s_branch .Lstg4_loop
.Lstg4_done:
	s_branch .LBB9_497
.Lgb3_orig:
	s_add_i32 s2, 0, 0x24000
	v_mov_b32_e32 v0, s2
	s_waitcnt vmcnt(0) expcnt(0) lgkmcnt(0)
	ds_read_b32 v2, v0
	s_add_i32 s2, 0, 0x24004
	v_mov_b32_e32 v0, s2
	ds_read_b32 v0, v0
	s_waitcnt lgkmcnt(1)
	v_cmp_ne_u32_e32 vcc, 0, v2
	s_cbranch_vccnz .LBB9_461
	s_add_u32 s6, s90, 0x1000
	s_addc_u32 s7, s91, 0
	s_add_u32 s8, s90, 0x1100
	s_addc_u32 s9, s91, 0
	s_add_u32 s10, s90, 0x1200
	s_addc_u32 s11, s91, 0
	s_mul_i32 s18, s95, s83
	s_add_u32 s12, s90, 0x1300
	s_mul_i32 s18, s18, s94
	s_addc_u32 s13, s91, 0
	s_mov_b32 s19, 1
	v_mov_b32_e32 v16, 0
	s_branch .LBB9_449
